# MLA prefetch: uniform 64-bit address terms folded with SALU adds, one VALU per lane address
# speedup vs baseline: 1.0074x; 1.0074x over previous
; template <int NT, int DQK, int DV, int MODE, int PD, class Src> ...
;     ...
;         if (kc + PD < kc1) ABL_LOAD(u, kc + PD);
.LBB0_766:
	s_add_u32 vcc_lo, s40, 0x16060000
	s_addc_u32 vcc_hi, s41, 0
	v_lshl_add_u64 v[34:35], v[216:217], 0, vcc
	global_load_dwordx4 v[34:37], v[34:35], off offset:128

.LBB0_778:
	s_andn2_saveexec_b64 s[22:23], s[22:23]
	s_cbranch_execz .LBB0_780
	s_add_u32 vcc_lo, s40, s78
	s_addc_u32 vcc_hi, s41, s79
	v_lshl_add_u64 v[26:27], v[212:213], 0, vcc

.LBB0_783:
	s_andn2_saveexec_b64 s[22:23], s[22:23]
	s_cbranch_execz .LBB0_785
	s_add_u32 vcc_lo, s40, s78
	s_addc_u32 vcc_hi, s41, s79
	v_lshl_add_u64 v[30:31], v[214:215], 0, vcc

.LBB0_808:
	s_add_u32 vcc_lo, s40, 0x16080000
	s_addc_u32 vcc_hi, s41, 0
	v_lshl_add_u64 v[42:43], v[216:217], 0, vcc
	global_load_dwordx4 v[42:45], v[42:43], off offset:128

.LBB0_818:
	s_andn2_saveexec_b64 s[22:23], s[22:23]
	s_cbranch_execz .LBB0_820
	s_add_u32 s74, s40, 0x16080000
	s_addc_u32 s75, s41, 0
	v_lshl_add_u64 v[38:39], v[212:213], 0, s[74:75]

.LBB0_823:
	s_andn2_saveexec_b64 s[22:23], s[22:23]
	s_cbranch_execz .LBB0_825
	s_add_u32 s8, s40, 0x16080000
	s_addc_u32 s9, s41, 0
	v_lshl_add_u64 v[46:47], v[214:215], 0, s[8:9]

.LBB0_848:
	s_add_u32 vcc_lo, s40, 0x160a0000
	s_addc_u32 vcc_hi, s41, 0
	v_lshl_add_u64 v[54:55], v[216:217], 0, vcc
	global_load_dwordx4 v[54:57], v[54:55], off offset:128

.LBB0_858:
	s_andn2_saveexec_b64 s[22:23], s[22:23]
	s_cbranch_execz .LBB0_860
	s_add_u32 s72, s40, 0x160a0000
	s_addc_u32 s73, s41, 0
	v_lshl_add_u64 v[50:51], v[212:213], 0, s[72:73]

.LBB0_863:
	s_andn2_saveexec_b64 s[22:23], s[22:23]
	s_cbranch_execz .LBB0_865
	s_add_u32 s8, s40, 0x160a0000
	s_addc_u32 s9, s41, 0
	v_lshl_add_u64 v[58:59], v[214:215], 0, s[8:9]

.LBB0_939:
	s_add_u32 vcc_lo, s66, 0x16060000
	s_addc_u32 vcc_hi, s67, 0
	v_lshl_add_u64 v[34:35], v[216:217], 0, vcc
	global_load_dwordx4 v[34:37], v[34:35], off offset:128

.LBB0_951:
	s_andn2_saveexec_b64 s[22:23], s[22:23]
	s_cbranch_execz .LBB0_953
	s_add_u32 vcc_lo, s66, s78
	s_addc_u32 vcc_hi, s67, s79
	v_lshl_add_u64 v[26:27], v[212:213], 0, vcc

.LBB0_956:
	s_andn2_saveexec_b64 s[22:23], s[22:23]
	s_cbranch_execz .LBB0_958
	s_add_u32 vcc_lo, s66, s78
	s_addc_u32 vcc_hi, s67, s79
	v_lshl_add_u64 v[30:31], v[214:215], 0, vcc

.LBB0_981:
	s_add_u32 vcc_lo, s66, 0x16080000
	s_addc_u32 vcc_hi, s67, 0
	v_lshl_add_u64 v[42:43], v[216:217], 0, vcc
	global_load_dwordx4 v[42:45], v[42:43], off offset:128

.LBB0_991:
	s_andn2_saveexec_b64 s[22:23], s[22:23]
	s_cbranch_execz .LBB0_993
	s_add_u32 s68, s66, 0x16080000
	s_addc_u32 s69, s67, 0
	v_lshl_add_u64 v[38:39], v[212:213], 0, s[68:69]

.LBB0_996:
	s_andn2_saveexec_b64 s[22:23], s[22:23]
	s_cbranch_execz .LBB0_998
	s_add_u32 s8, s66, 0x16080000
	s_addc_u32 s9, s67, 0
	v_lshl_add_u64 v[46:47], v[214:215], 0, s[8:9]

.LBB0_1021:
	s_add_u32 vcc_lo, s66, 0x160a0000
	s_addc_u32 vcc_hi, s67, 0
	v_lshl_add_u64 v[54:55], v[216:217], 0, vcc
	global_load_dwordx4 v[54:57], v[54:55], off offset:128

.LBB0_1031:
	s_andn2_saveexec_b64 s[22:23], s[22:23]
	s_cbranch_execz .LBB0_1033
	s_add_u32 s58, s66, 0x160a0000
	s_addc_u32 s59, s67, 0
	v_lshl_add_u64 v[50:51], v[212:213], 0, s[58:59]

.LBB0_1036:
	s_andn2_saveexec_b64 s[22:23], s[22:23]
	s_cbranch_execz .LBB0_1038
	s_add_u32 s8, s66, 0x160a0000
	s_addc_u32 s9, s67, 0
	v_lshl_add_u64 v[58:59], v[214:215], 0, s[8:9]
